# ML_OUT / ML_LOC / MLA unit epilogue: 15 v_max(x,x) canonicalisations removed (readers take x directly)
# speedup vs baseline: 1.0086x; 1.0055x over previous
; __device__ __forceinline__ int crow(int r, int hi) { return (r & 3) + 8 * (r >> 2) + 4 * hi; }
; __device__ __forceinline__ void ml_out_phase(const bf16_t* P, const float* GATES, const float* cw, const float* b_i, const float* b_f, const float* gain, const float* KV, const float* MPREV, bf16_t* GO, LAS unsigned char* lds) {
;     ...
;         for (int r = 0; r < 16; ++r) { const int tl = crow(r, hi), tr = 32 * th + tl; const float num = o[r] + aL[tr] * oc[r], dn = denw[wid * 32 + tl];
;             hv[r] = num / fmaxf(fabsf(dn), emL[tr]);
;             float s = hv[r] * hv[r];
; #pragma unroll
;             for (int of = 1; of < 32; of <<= 1) s += __shfl_xor(s, of);
;             if (q32 == 0) ssqw[(th * 4 + dq) * 32 + tl] = s; }
.LBB0_209:
	s_or_b64 exec, exec, s[6:7]
	s_waitcnt lgkmcnt(0)
	ds_read2_b32 v[96:97], v149 offset0:129 offset1:193
	ds_read_b32 v1, v145 offset:1284
	s_waitcnt lgkmcnt(1)
	v_fmac_f32_e32 v3, v19, v96
	s_waitcnt lgkmcnt(0)
	v_max_f32_e64 v1, |v1|, |v1|
	v_max_f32_e32 v1, v1, v97
	v_div_scale_f32 v19, s[4:5], v1, v1, v3
	v_rcp_f32_e32 v96, v19
	v_div_scale_f32 v97, vcc, v3, v1, v3
	v_fma_f32 v98, -v19, v96, 1.0
	v_fmac_f32_e32 v96, v98, v96
	v_mul_f32_e32 v98, v97, v96
	v_fma_f32 v99, -v19, v98, v97
	v_fmac_f32_e32 v98, v99, v96
	v_fma_f32 v19, -v19, v98, v97
	v_div_fmas_f32 v19, v19, v96, v98
	v_div_fixup_f32 v168, v19, v1, v3
	v_mul_f32_e32 v1, v168, v168
	ds_bpermute_b32 v1, v18, v1
	s_waitcnt lgkmcnt(0)
	v_fmac_f32_e32 v1, v168, v168
	ds_bpermute_b32 v3, v2, v1
	s_waitcnt lgkmcnt(0)
	v_add_f32_e32 v1, v1, v3
	ds_bpermute_b32 v3, v104, v1
	s_waitcnt lgkmcnt(0)
	v_add_f32_e32 v1, v1, v3
	ds_bpermute_b32 v3, v105, v1
	s_waitcnt lgkmcnt(0)
	v_add_f32_e32 v1, v1, v3
	ds_bpermute_b32 v3, v106, v1
	s_and_saveexec_b64 s[6:7], s[44:45]
	s_cbranch_execz .LBB0_211
	s_waitcnt lgkmcnt(0)
	v_add_f32_e32 v1, v1, v3
	ds_write_b32 v147, v1 offset:2308
.LBB0_211:
	s_or_b64 exec, exec, s[6:7]
	ds_read2_b32 v[96:97], v149 offset0:130 offset1:194
	ds_read_b32 v1, v145 offset:1288
	s_waitcnt lgkmcnt(1)
	s_waitcnt lgkmcnt(0)
	v_max_f32_e64 v1, |v1|, |v1|
	v_fmac_f32_e32 v4, v20, v96
	v_max_f32_e32 v1, v1, v97
	v_div_scale_f32 v3, s[4:5], v1, v1, v4
	v_rcp_f32_e32 v19, v3
	v_div_scale_f32 v20, vcc, v4, v1, v4
	v_fma_f32 v96, -v3, v19, 1.0
	v_fmac_f32_e32 v19, v96, v19
	v_mul_f32_e32 v96, v20, v19
	v_fma_f32 v97, -v3, v96, v20
	v_fmac_f32_e32 v96, v97, v19
	v_fma_f32 v3, -v3, v96, v20
	v_div_fmas_f32 v3, v3, v19, v96
	v_div_fixup_f32 v169, v3, v1, v4
	v_mul_f32_e32 v1, v169, v169
	ds_bpermute_b32 v1, v18, v1
	s_waitcnt lgkmcnt(0)
	v_fmac_f32_e32 v1, v169, v169
	ds_bpermute_b32 v3, v2, v1
	s_waitcnt lgkmcnt(0)
	v_add_f32_e32 v1, v1, v3
	ds_bpermute_b32 v3, v104, v1
	s_waitcnt lgkmcnt(0)
	v_add_f32_e32 v1, v1, v3
	ds_bpermute_b32 v3, v105, v1
	s_waitcnt lgkmcnt(0)
	v_add_f32_e32 v1, v1, v3
	ds_bpermute_b32 v3, v106, v1
	s_and_saveexec_b64 s[6:7], s[44:45]
	s_cbranch_execz .LBB0_213
	s_waitcnt lgkmcnt(0)
	v_add_f32_e32 v1, v1, v3
	ds_write_b32 v147, v1 offset:2312
.LBB0_213:
	s_or_b64 exec, exec, s[6:7]
	ds_read2_b32 v[96:97], v149 offset0:131 offset1:195
	ds_read_b32 v1, v145 offset:1292
	s_waitcnt lgkmcnt(1)
	s_waitcnt lgkmcnt(0)
	v_max_f32_e64 v1, |v1|, |v1|
	v_fmac_f32_e32 v5, v21, v96
	v_max_f32_e32 v1, v1, v97
	v_div_scale_f32 v3, s[4:5], v1, v1, v5
	v_rcp_f32_e32 v4, v3
	v_div_scale_f32 v19, vcc, v5, v1, v5
	v_fma_f32 v20, -v3, v4, 1.0
	v_fmac_f32_e32 v4, v20, v4
	v_mul_f32_e32 v20, v19, v4
	v_fma_f32 v21, -v3, v20, v19
	v_fmac_f32_e32 v20, v21, v4
	v_fma_f32 v3, -v3, v20, v19
	v_div_fmas_f32 v3, v3, v4, v20
	v_div_fixup_f32 v170, v3, v1, v5
	v_mul_f32_e32 v1, v170, v170
	ds_bpermute_b32 v1, v18, v1
	s_waitcnt lgkmcnt(0)
	v_fmac_f32_e32 v1, v170, v170
	ds_bpermute_b32 v3, v2, v1
	s_waitcnt lgkmcnt(0)
	v_add_f32_e32 v1, v1, v3
	ds_bpermute_b32 v3, v104, v1
	s_waitcnt lgkmcnt(0)
	v_add_f32_e32 v1, v1, v3
	ds_bpermute_b32 v3, v105, v1
	s_waitcnt lgkmcnt(0)
	v_add_f32_e32 v1, v1, v3
	ds_bpermute_b32 v3, v106, v1
	s_and_saveexec_b64 s[6:7], s[44:45]
	s_cbranch_execz .LBB0_215
	s_waitcnt lgkmcnt(0)
	v_add_f32_e32 v1, v1, v3
	ds_write_b32 v147, v1 offset:2316
.LBB0_215:
	s_or_b64 exec, exec, s[6:7]
	ds_read2_b32 v[4:5], v149 offset0:136 offset1:200
	ds_read_b32 v1, v145 offset:1312
	s_waitcnt lgkmcnt(1)
	s_waitcnt lgkmcnt(0)
	v_max_f32_e64 v1, |v1|, |v1|
	v_fmac_f32_e32 v6, v22, v4
	v_max_f32_e32 v1, v1, v5
	v_div_scale_f32 v3, s[4:5], v1, v1, v6
	v_rcp_f32_e32 v4, v3
	v_div_scale_f32 v5, vcc, v6, v1, v6
	v_fma_f32 v19, -v3, v4, 1.0
	v_fmac_f32_e32 v4, v19, v4
	v_mul_f32_e32 v19, v5, v4
	v_fma_f32 v20, -v3, v19, v5
	v_fmac_f32_e32 v19, v20, v4
	v_fma_f32 v3, -v3, v19, v5
	v_div_fmas_f32 v3, v3, v4, v19
	v_div_fixup_f32 v103, v3, v1, v6
	v_mul_f32_e32 v1, v103, v103
	ds_bpermute_b32 v1, v18, v1
	s_waitcnt lgkmcnt(0)
	v_fmac_f32_e32 v1, v103, v103
	ds_bpermute_b32 v3, v2, v1
	s_waitcnt lgkmcnt(0)
	v_add_f32_e32 v1, v1, v3
	ds_bpermute_b32 v3, v104, v1
	s_waitcnt lgkmcnt(0)
	v_add_f32_e32 v1, v1, v3
	ds_bpermute_b32 v3, v105, v1
	s_waitcnt lgkmcnt(0)
	v_add_f32_e32 v1, v1, v3
	ds_bpermute_b32 v3, v106, v1
	s_and_saveexec_b64 s[6:7], s[44:45]
	s_cbranch_execz .LBB0_217
	s_waitcnt lgkmcnt(0)
	v_add_f32_e32 v1, v1, v3
	ds_write_b32 v147, v1 offset:2336
.LBB0_217:
	s_or_b64 exec, exec, s[6:7]
	ds_read2_b32 v[4:5], v149 offset0:137 offset1:201
	ds_read_b32 v1, v145 offset:1316
	s_waitcnt lgkmcnt(1)
	s_waitcnt lgkmcnt(0)
	v_max_f32_e64 v1, |v1|, |v1|
	v_fmac_f32_e32 v7, v23, v4
	v_max_f32_e32 v1, v1, v5
	v_div_scale_f32 v3, s[4:5], v1, v1, v7
	v_rcp_f32_e32 v4, v3
	v_div_scale_f32 v5, vcc, v7, v1, v7
	v_fma_f32 v6, -v3, v4, 1.0
	v_fmac_f32_e32 v4, v6, v4
	v_mul_f32_e32 v6, v5, v4
	v_fma_f32 v19, -v3, v6, v5
	v_fmac_f32_e32 v6, v19, v4
	v_fma_f32 v3, -v3, v6, v5
	v_div_fmas_f32 v3, v3, v4, v6
	v_div_fixup_f32 v102, v3, v1, v7
	v_mul_f32_e32 v1, v102, v102
	ds_bpermute_b32 v1, v18, v1
	s_waitcnt lgkmcnt(0)
	v_fmac_f32_e32 v1, v102, v102
	ds_bpermute_b32 v3, v2, v1
	s_waitcnt lgkmcnt(0)
	v_add_f32_e32 v1, v1, v3
	ds_bpermute_b32 v3, v104, v1
	s_waitcnt lgkmcnt(0)
	v_add_f32_e32 v1, v1, v3
	ds_bpermute_b32 v3, v105, v1
	s_waitcnt lgkmcnt(0)
	v_add_f32_e32 v1, v1, v3
	ds_bpermute_b32 v3, v106, v1
	s_and_saveexec_b64 s[6:7], s[44:45]
	s_cbranch_execz .LBB0_219
	s_waitcnt lgkmcnt(0)
	v_add_f32_e32 v1, v1, v3
	ds_write_b32 v147, v1 offset:2340
; __device__ __forceinline__ int crow(int r, int hi) { return (r & 3) + 8 * (r >> 2) + 4 * hi; }
; __device__ __forceinline__ void ml_out_phase(const bf16_t* P, const float* GATES, const float* cw, const float* b_i, const float* b_f, const float* gain, const float* KV, const float* MPREV, bf16_t* GO, LAS unsigned char* lds) {
;     ...
;         for (int r = 0; r < 16; ++r) { const int tl = crow(r, hi), tr = 32 * th + tl; const float num = o[r] + aL[tr] * oc[r], dn = denw[wid * 32 + tl];
;             hv[r] = num / fmaxf(fabsf(dn), emL[tr]);
;             float s = hv[r] * hv[r];
; #pragma unroll
;             for (int of = 1; of < 32; of <<= 1) s += __shfl_xor(s, of);
;             if (q32 == 0) ssqw[(th * 4 + dq) * 32 + tl] = s; }
.LBB0_219:
	s_or_b64 exec, exec, s[6:7]
	ds_read2_b32 v[4:5], v149 offset0:138 offset1:202
	ds_read_b32 v1, v145 offset:1320
	s_waitcnt lgkmcnt(1)
	s_waitcnt lgkmcnt(0)
	v_max_f32_e64 v1, |v1|, |v1|
	v_fmac_f32_e32 v8, v24, v4
	v_max_f32_e32 v1, v1, v5
	v_div_scale_f32 v3, s[4:5], v1, v1, v8
	v_rcp_f32_e32 v4, v3
	v_div_scale_f32 v5, vcc, v8, v1, v8
	v_fma_f32 v6, -v3, v4, 1.0
	v_fmac_f32_e32 v4, v6, v4
	v_mul_f32_e32 v6, v5, v4
	v_fma_f32 v7, -v3, v6, v5
	v_fmac_f32_e32 v6, v7, v4
	v_fma_f32 v3, -v3, v6, v5
	v_div_fmas_f32 v3, v3, v4, v6
	v_div_fixup_f32 v101, v3, v1, v8
	v_mul_f32_e32 v1, v101, v101
	ds_bpermute_b32 v1, v18, v1
	s_waitcnt lgkmcnt(0)
	v_fmac_f32_e32 v1, v101, v101
	ds_bpermute_b32 v3, v2, v1
	s_waitcnt lgkmcnt(0)
	v_add_f32_e32 v1, v1, v3
	ds_bpermute_b32 v3, v104, v1
	s_waitcnt lgkmcnt(0)
	v_add_f32_e32 v1, v1, v3
	ds_bpermute_b32 v3, v105, v1
	s_waitcnt lgkmcnt(0)
	v_add_f32_e32 v1, v1, v3
	ds_bpermute_b32 v3, v106, v1
	s_and_saveexec_b64 s[6:7], s[44:45]
	s_cbranch_execz .LBB0_221
	s_waitcnt lgkmcnt(0)
	v_add_f32_e32 v1, v1, v3
	ds_write_b32 v147, v1 offset:2344
.LBB0_221:
	s_or_b64 exec, exec, s[6:7]
	ds_read2_b32 v[4:5], v149 offset0:139 offset1:203
	ds_read_b32 v1, v145 offset:1324
	s_waitcnt lgkmcnt(1)
	s_waitcnt lgkmcnt(0)
	v_max_f32_e64 v1, |v1|, |v1|
	v_fmac_f32_e32 v9, v25, v4
	v_max_f32_e32 v1, v1, v5
	v_div_scale_f32 v3, s[4:5], v1, v1, v9
	v_rcp_f32_e32 v4, v3
	v_div_scale_f32 v5, vcc, v9, v1, v9
	v_fma_f32 v6, -v3, v4, 1.0
	v_fmac_f32_e32 v4, v6, v4
	v_mul_f32_e32 v6, v5, v4
	v_fma_f32 v7, -v3, v6, v5
	v_fmac_f32_e32 v6, v7, v4
	v_fma_f32 v3, -v3, v6, v5
	v_div_fmas_f32 v3, v3, v4, v6
	v_div_fixup_f32 v100, v3, v1, v9
	v_mul_f32_e32 v1, v100, v100
	ds_bpermute_b32 v1, v18, v1
	s_waitcnt lgkmcnt(0)
	v_fmac_f32_e32 v1, v100, v100
	ds_bpermute_b32 v3, v2, v1
	s_waitcnt lgkmcnt(0)
	v_add_f32_e32 v1, v1, v3
	ds_bpermute_b32 v3, v104, v1
	s_waitcnt lgkmcnt(0)
	v_add_f32_e32 v1, v1, v3
	ds_bpermute_b32 v3, v105, v1
	s_waitcnt lgkmcnt(0)
	v_add_f32_e32 v1, v1, v3
	ds_bpermute_b32 v3, v106, v1
	s_and_saveexec_b64 s[6:7], s[44:45]
	s_cbranch_execz .LBB0_223
	s_waitcnt lgkmcnt(0)
	v_add_f32_e32 v1, v1, v3
	ds_write_b32 v147, v1 offset:2348
.LBB0_223:
	s_or_b64 exec, exec, s[6:7]
	ds_read2_b32 v[4:5], v149 offset0:144 offset1:208
	ds_read_b32 v1, v145 offset:1344
	s_waitcnt lgkmcnt(1)
	s_waitcnt lgkmcnt(0)
	v_max_f32_e64 v1, |v1|, |v1|
	v_fmac_f32_e32 v10, v26, v4
	v_max_f32_e32 v1, v1, v5
	v_div_scale_f32 v3, s[4:5], v1, v1, v10
	v_rcp_f32_e32 v4, v3
	v_div_scale_f32 v5, vcc, v10, v1, v10
	v_fma_f32 v6, -v3, v4, 1.0
	v_fmac_f32_e32 v4, v6, v4
	v_mul_f32_e32 v6, v5, v4
	v_fma_f32 v7, -v3, v6, v5
	v_fmac_f32_e32 v6, v7, v4
	v_fma_f32 v3, -v3, v6, v5
	v_div_fmas_f32 v3, v3, v4, v6
	v_div_fixup_f32 v96, v3, v1, v10
	v_mul_f32_e32 v1, v96, v96
	ds_bpermute_b32 v1, v18, v1
	s_waitcnt lgkmcnt(0)
	v_fmac_f32_e32 v1, v96, v96
	ds_bpermute_b32 v3, v2, v1
	s_waitcnt lgkmcnt(0)
	v_add_f32_e32 v1, v1, v3
	ds_bpermute_b32 v3, v104, v1
	s_waitcnt lgkmcnt(0)
	v_add_f32_e32 v1, v1, v3
	ds_bpermute_b32 v3, v105, v1
	s_waitcnt lgkmcnt(0)
	v_add_f32_e32 v1, v1, v3
	ds_bpermute_b32 v3, v106, v1
	s_and_saveexec_b64 s[6:7], s[44:45]
	s_cbranch_execz .LBB0_225
	s_waitcnt lgkmcnt(0)
	v_add_f32_e32 v1, v1, v3
	ds_write_b32 v147, v1 offset:2368
.LBB0_225:
	s_or_b64 exec, exec, s[6:7]
	ds_read2_b32 v[4:5], v149 offset0:145 offset1:209
	ds_read_b32 v1, v145 offset:1348
	s_waitcnt lgkmcnt(1)
	s_waitcnt lgkmcnt(0)
	v_max_f32_e64 v1, |v1|, |v1|
	v_fmac_f32_e32 v11, v27, v4
	v_max_f32_e32 v1, v1, v5
	v_div_scale_f32 v3, s[4:5], v1, v1, v11
	v_rcp_f32_e32 v4, v3
	v_div_scale_f32 v5, vcc, v11, v1, v11
	v_fma_f32 v6, -v3, v4, 1.0
	v_fmac_f32_e32 v4, v6, v4
	v_mul_f32_e32 v6, v5, v4
	v_fma_f32 v7, -v3, v6, v5
	v_fmac_f32_e32 v6, v7, v4
	v_fma_f32 v3, -v3, v6, v5
	v_div_fmas_f32 v3, v3, v4, v6
	v_div_fixup_f32 v97, v3, v1, v11
	v_mul_f32_e32 v1, v97, v97
	ds_bpermute_b32 v1, v18, v1
	s_waitcnt lgkmcnt(0)
	v_fmac_f32_e32 v1, v97, v97
	ds_bpermute_b32 v3, v2, v1
	s_waitcnt lgkmcnt(0)
	v_add_f32_e32 v1, v1, v3
	ds_bpermute_b32 v3, v104, v1
	s_waitcnt lgkmcnt(0)
	v_add_f32_e32 v1, v1, v3
	ds_bpermute_b32 v3, v105, v1
	s_waitcnt lgkmcnt(0)
	v_add_f32_e32 v1, v1, v3
	ds_bpermute_b32 v3, v106, v1
	s_and_saveexec_b64 s[6:7], s[44:45]
	s_cbranch_execz .LBB0_227
	s_waitcnt lgkmcnt(0)
	v_add_f32_e32 v1, v1, v3
	ds_write_b32 v147, v1 offset:2372
.LBB0_227:
	s_or_b64 exec, exec, s[6:7]
	ds_read2_b32 v[4:5], v149 offset0:146 offset1:210
	ds_read_b32 v1, v145 offset:1352
	s_waitcnt lgkmcnt(1)
	s_waitcnt lgkmcnt(0)
	v_max_f32_e64 v1, |v1|, |v1|
	v_fmac_f32_e32 v12, v28, v4
	v_max_f32_e32 v1, v1, v5
	v_div_scale_f32 v3, s[4:5], v1, v1, v12
	v_rcp_f32_e32 v4, v3
	v_div_scale_f32 v5, vcc, v12, v1, v12
	v_fma_f32 v6, -v3, v4, 1.0
	v_fmac_f32_e32 v4, v6, v4
	v_mul_f32_e32 v6, v5, v4
	v_fma_f32 v7, -v3, v6, v5
	v_fmac_f32_e32 v6, v7, v4
	v_fma_f32 v3, -v3, v6, v5
	v_div_fmas_f32 v3, v3, v4, v6
	v_div_fixup_f32 v98, v3, v1, v12
	v_mul_f32_e32 v1, v98, v98
	ds_bpermute_b32 v1, v18, v1
	s_waitcnt lgkmcnt(0)
	v_fmac_f32_e32 v1, v98, v98
	ds_bpermute_b32 v3, v2, v1
	s_waitcnt lgkmcnt(0)
	v_add_f32_e32 v1, v1, v3
	ds_bpermute_b32 v3, v104, v1
	s_waitcnt lgkmcnt(0)
	v_add_f32_e32 v1, v1, v3
	ds_bpermute_b32 v3, v105, v1
	s_waitcnt lgkmcnt(0)
	v_add_f32_e32 v1, v1, v3
	ds_bpermute_b32 v3, v106, v1
	s_and_saveexec_b64 s[6:7], s[44:45]
	s_cbranch_execz .LBB0_229
	s_waitcnt lgkmcnt(0)
	v_add_f32_e32 v1, v1, v3
	ds_write_b32 v147, v1 offset:2376
; __device__ __forceinline__ int crow(int r, int hi) { return (r & 3) + 8 * (r >> 2) + 4 * hi; }
; __device__ __forceinline__ void ml_out_phase(const bf16_t* P, const float* GATES, const float* cw, const float* b_i, const float* b_f, const float* gain, const float* KV, const float* MPREV, bf16_t* GO, LAS unsigned char* lds) {
;     ...
;         for (int r = 0; r < 16; ++r) { const int tl = crow(r, hi), tr = 32 * th + tl; const float num = o[r] + aL[tr] * oc[r], dn = denw[wid * 32 + tl];
;             hv[r] = num / fmaxf(fabsf(dn), emL[tr]);
;             float s = hv[r] * hv[r];
; #pragma unroll
;             for (int of = 1; of < 32; of <<= 1) s += __shfl_xor(s, of);
;             if (q32 == 0) ssqw[(th * 4 + dq) * 32 + tl] = s; }
.LBB0_229:
	s_or_b64 exec, exec, s[6:7]
	ds_read2_b32 v[4:5], v149 offset0:147 offset1:211
	ds_read_b32 v1, v145 offset:1356
	s_waitcnt lgkmcnt(1)
	s_waitcnt lgkmcnt(0)
	v_max_f32_e64 v1, |v1|, |v1|
	v_fmac_f32_e32 v13, v29, v4
	v_max_f32_e32 v1, v1, v5
	v_div_scale_f32 v3, s[4:5], v1, v1, v13
	v_rcp_f32_e32 v4, v3
	v_div_scale_f32 v5, vcc, v13, v1, v13
	v_fma_f32 v6, -v3, v4, 1.0
	v_fmac_f32_e32 v4, v6, v4
	v_mul_f32_e32 v6, v5, v4
	v_fma_f32 v7, -v3, v6, v5
	v_fmac_f32_e32 v6, v7, v4
	v_fma_f32 v3, -v3, v6, v5
	v_div_fmas_f32 v3, v3, v4, v6
	v_div_fixup_f32 v99, v3, v1, v13
	v_mul_f32_e32 v1, v99, v99
	ds_bpermute_b32 v1, v18, v1
	s_waitcnt lgkmcnt(0)
	v_fmac_f32_e32 v1, v99, v99
	ds_bpermute_b32 v3, v2, v1
	s_waitcnt lgkmcnt(0)
	v_add_f32_e32 v1, v1, v3
	ds_bpermute_b32 v3, v104, v1
	s_waitcnt lgkmcnt(0)
	v_add_f32_e32 v1, v1, v3
	ds_bpermute_b32 v3, v105, v1
	s_waitcnt lgkmcnt(0)
	v_add_f32_e32 v1, v1, v3
	ds_bpermute_b32 v3, v106, v1
	s_and_saveexec_b64 s[6:7], s[44:45]
	s_cbranch_execz .LBB0_231
	s_waitcnt lgkmcnt(0)
	v_add_f32_e32 v1, v1, v3
	ds_write_b32 v147, v1 offset:2380
.LBB0_231:
	s_or_b64 exec, exec, s[6:7]
	ds_read2_b32 v[4:5], v149 offset0:152 offset1:216
	ds_read_b32 v1, v145 offset:1376
	s_waitcnt lgkmcnt(1)
	s_waitcnt lgkmcnt(0)
	v_max_f32_e64 v1, |v1|, |v1|
	v_fmac_f32_e32 v14, v30, v4
	v_max_f32_e32 v1, v1, v5
	v_div_scale_f32 v3, s[4:5], v1, v1, v14
	v_rcp_f32_e32 v4, v3
	v_div_scale_f32 v5, vcc, v14, v1, v14
	v_fma_f32 v6, -v3, v4, 1.0
	v_fmac_f32_e32 v4, v6, v4
	v_mul_f32_e32 v6, v5, v4
	v_fma_f32 v7, -v3, v6, v5
	v_fmac_f32_e32 v6, v7, v4
	v_fma_f32 v3, -v3, v6, v5
	v_div_fmas_f32 v3, v3, v4, v6
	v_div_fixup_f32 v24, v3, v1, v14
	v_mul_f32_e32 v1, v24, v24
	ds_bpermute_b32 v1, v18, v1
	s_waitcnt lgkmcnt(0)
	v_fmac_f32_e32 v1, v24, v24
	ds_bpermute_b32 v3, v2, v1
	s_waitcnt lgkmcnt(0)
	v_add_f32_e32 v1, v1, v3
	ds_bpermute_b32 v3, v104, v1
	s_waitcnt lgkmcnt(0)
	v_add_f32_e32 v1, v1, v3
	ds_bpermute_b32 v3, v105, v1
	s_waitcnt lgkmcnt(0)
	v_add_f32_e32 v1, v1, v3
	ds_bpermute_b32 v3, v106, v1
	s_and_saveexec_b64 s[6:7], s[44:45]
	s_cbranch_execz .LBB0_233
	s_waitcnt lgkmcnt(0)
	v_add_f32_e32 v1, v1, v3
	ds_write_b32 v147, v1 offset:2400
.LBB0_233:
	s_or_b64 exec, exec, s[6:7]
	ds_read2_b32 v[4:5], v149 offset0:153 offset1:217
	ds_read_b32 v1, v145 offset:1380
	s_waitcnt lgkmcnt(1)
	s_waitcnt lgkmcnt(0)
	v_max_f32_e64 v1, |v1|, |v1|
	v_fmac_f32_e32 v15, v31, v4
	v_max_f32_e32 v1, v1, v5
	v_div_scale_f32 v3, s[4:5], v1, v1, v15
	v_rcp_f32_e32 v4, v3
	v_div_scale_f32 v5, vcc, v15, v1, v15
	v_fma_f32 v6, -v3, v4, 1.0
	v_fmac_f32_e32 v4, v6, v4
	v_mul_f32_e32 v6, v5, v4
	v_fma_f32 v7, -v3, v6, v5
	v_fmac_f32_e32 v6, v7, v4
	v_fma_f32 v3, -v3, v6, v5
	v_div_fmas_f32 v3, v3, v4, v6
	v_div_fixup_f32 v23, v3, v1, v15
	v_mul_f32_e32 v1, v23, v23
	ds_bpermute_b32 v1, v18, v1
	s_waitcnt lgkmcnt(0)
	v_fmac_f32_e32 v1, v23, v23
	ds_bpermute_b32 v3, v2, v1
	s_waitcnt lgkmcnt(0)
	v_add_f32_e32 v1, v1, v3
	ds_bpermute_b32 v3, v104, v1
	s_waitcnt lgkmcnt(0)
	v_add_f32_e32 v1, v1, v3
	ds_bpermute_b32 v3, v105, v1
	s_waitcnt lgkmcnt(0)
	v_add_f32_e32 v1, v1, v3
	ds_bpermute_b32 v3, v106, v1
	s_and_saveexec_b64 s[6:7], s[44:45]
	s_cbranch_execz .LBB0_235
	s_waitcnt lgkmcnt(0)
	v_add_f32_e32 v1, v1, v3
	ds_write_b32 v147, v1 offset:2404
.LBB0_235:
	s_or_b64 exec, exec, s[6:7]
	ds_read2_b32 v[4:5], v149 offset0:154 offset1:218
	ds_read_b32 v1, v145 offset:1384
	s_waitcnt lgkmcnt(1)
	s_waitcnt lgkmcnt(0)
	v_max_f32_e64 v1, |v1|, |v1|
	v_fmac_f32_e32 v16, v32, v4
	v_max_f32_e32 v1, v1, v5
	v_div_scale_f32 v3, s[4:5], v1, v1, v16
	v_rcp_f32_e32 v4, v3
	v_div_scale_f32 v5, vcc, v16, v1, v16
	v_fma_f32 v6, -v3, v4, 1.0
	v_fmac_f32_e32 v4, v6, v4
	v_mul_f32_e32 v6, v5, v4
	v_fma_f32 v7, -v3, v6, v5
	v_fmac_f32_e32 v6, v7, v4
	v_fma_f32 v3, -v3, v6, v5
	v_div_fmas_f32 v3, v3, v4, v6
	v_div_fixup_f32 v21, v3, v1, v16
	v_mul_f32_e32 v1, v21, v21
	ds_bpermute_b32 v1, v18, v1
	s_waitcnt lgkmcnt(0)
	v_fmac_f32_e32 v1, v21, v21
	ds_bpermute_b32 v3, v2, v1
	s_waitcnt lgkmcnt(0)
	v_add_f32_e32 v1, v1, v3
	ds_bpermute_b32 v3, v104, v1
	s_waitcnt lgkmcnt(0)
	v_add_f32_e32 v1, v1, v3
	ds_bpermute_b32 v3, v105, v1
	s_waitcnt lgkmcnt(0)
	v_add_f32_e32 v1, v1, v3
	ds_bpermute_b32 v3, v106, v1
	s_and_saveexec_b64 s[6:7], s[44:45]
	s_cbranch_execz .LBB0_237
	s_waitcnt lgkmcnt(0)
	v_add_f32_e32 v1, v1, v3
	ds_write_b32 v147, v1 offset:2408
.LBB0_237:
	s_or_b64 exec, exec, s[6:7]
	ds_read2_b32 v[4:5], v149 offset0:155 offset1:219
	ds_read_b32 v1, v145 offset:1388
	s_waitcnt lgkmcnt(1)
	s_waitcnt lgkmcnt(0)
	v_max_f32_e64 v1, |v1|, |v1|
	v_fmac_f32_e32 v17, v33, v4
	v_max_f32_e32 v1, v1, v5
	v_div_scale_f32 v3, s[4:5], v1, v1, v17
	v_rcp_f32_e32 v4, v3
	v_div_scale_f32 v5, vcc, v17, v1, v17
	v_fma_f32 v6, -v3, v4, 1.0
	v_fmac_f32_e32 v4, v6, v4
	v_mul_f32_e32 v6, v5, v4
	v_fma_f32 v7, -v3, v6, v5
	v_fmac_f32_e32 v6, v7, v4
	v_fma_f32 v3, -v3, v6, v5
	v_div_fmas_f32 v3, v3, v4, v6
	v_div_fixup_f32 v1, v3, v1, v17
	v_mul_f32_e32 v3, v1, v1
	ds_bpermute_b32 v3, v18, v3
	s_waitcnt lgkmcnt(0)
	v_fmac_f32_e32 v3, v1, v1
	ds_bpermute_b32 v2, v2, v3
	s_waitcnt lgkmcnt(0)
	v_add_f32_e32 v2, v3, v2
	ds_bpermute_b32 v3, v104, v2
	s_waitcnt lgkmcnt(0)
	v_add_f32_e32 v2, v2, v3
	ds_bpermute_b32 v3, v105, v2
	s_waitcnt lgkmcnt(0)
	v_add_f32_e32 v2, v2, v3
	ds_bpermute_b32 v3, v106, v2
	s_and_saveexec_b64 s[6:7], s[44:45]
	s_cbranch_execz .LBB0_141
	s_waitcnt lgkmcnt(0)
	v_add_f32_e32 v2, v2, v3
	ds_write_b32 v147, v2 offset:2412
	s_branch .LBB0_141
